# P7a: half of the workgroups run the RG-LRU tiles before the delta-rule prep (bandwidth-bound prep overlaps latency-bound RG-LRU chip-wide); RG_SPLIT 6
# speedup vs baseline: 1.0116x; 1.0078x over previous
; #define LAS __attribute__((address_space(3)))
; #define INP(k) karg_in(k)
; #define tid opq((wave << 6) | lane_now())
; __global__ void __launch_bounds__(NTHR, 2) fwd_megakernel(Params P) {
;     ...
;     if constexpr ((PHM >> 7) & 1) {
;         { const int bh0 = (wg * NWAVES) >> 5, h0 = bh0 & 7; LAS float* w = (LAS float*)lds; const float* cwq = INP(22);
;           for (int i = tid; i < 1536; i += NTHR) { const int which = i >> 9, j = (i >> 7) & 3, d = i & 127; w[i] = cwq[(size_t)j * 3072 + which * 1024 + h0 * 128 + d]; }
;           __syncthreads();
.LBB0_1022:
	s_or_b64 exec, exec, s[4:5]
	s_waitcnt lgkmcnt(0)
	s_barrier
	s_mov_b32 s98, 0
	s_cmpk_lg_u32 s78, 0x100
	s_cbranch_scc1 .Lp7a_prep
	s_bitcmp1_b32 s2, 5
	s_cbranch_scc0 .Lp7a_prep
	s_mov_b32 s98, 1
	s_branch .Lp7a_rg
.Lp7a_prep:
	s_load_dwordx2 s[4:5], s[0:1], 0xb0
	v_mov_b32_e32 v0, v167
	s_movk_i32 s6, 0x600
	s_nop 0
	v_cmp_gt_i32_e32 vcc, s6, v0
	s_and_saveexec_b64 s[6:7], vcc
	s_cbranch_execz .LBB0_1035
	v_max_i32_e32 v1, 0x400, v0
	s_lshl_b32 s8, s2, 5
	v_sub_u32_e32 v1, v1, v0
	s_and_b32 s16, s8, 0x380
	s_movk_i32 s8, 0x1ff
	v_add_u32_e32 v1, 0x1ff, v1
	v_and_b32_e32 v8, 0x7f, v0
	v_mov_b32_e32 v4, 0
	v_cmp_lt_u32_e32 vcc, s8, v1
	s_mov_b64 s[10:11], -1
	s_and_saveexec_b64 s[8:9], vcc
	s_cbranch_execz .LBB0_1032
	v_lshrrev_b32_e32 v9, 9, v1
	v_add_u32_e32 v2, -1, v9
	v_add_u32_e32 v1, 0x200, v0
	v_lshrrev_b32_e32 v3, 1, v2
	v_add_u32_e32 v10, 1, v3
	v_cmp_lt_u32_e32 vcc, 5, v2
	v_mov_b64_e32 v[2:3], v[0:1]
	s_and_saveexec_b64 s[10:11], vcc
	s_cbranch_execz .LBB0_1028
	s_mov_b32 s13, 0
	v_mov_b32_e32 v5, 0
	v_and_b32_e32 v11, -4, v10
	v_lshl_add_u32 v12, v0, 2, 0
	s_mov_b64 s[14:15], 0
	s_lshl_b32 s12, s16, 2
	v_lshlrev_b32_e32 v6, 2, v8
	v_mov_b32_e32 v7, v5
	s_mov_b32 s17, s13
	v_mov_b64_e32 v[2:3], v[0:1]

; #define LAS __attribute__((address_space(3)))
; __device__ __forceinline__ void delta_prep_wave(const Params& P, LAS unsigned char* lds, int idx, int wave, int lane) {
;     ...
;     { int loff = hh * 1152;
;       float x[32];
; #pragma unroll
;       for (int i = 0; i < 32; ++i) { float sacc = (i == n) ? 1.f : 0.f;
;           const LAS float* Lb = Lm + loff;
; #pragma unroll
;           for (int j4 = 0; j4 < (i + 3) / 4; ++j4) { const f32x4 l = *(const LAS f32x4*)(Lb + i * 36 + 4 * j4);
; #pragma unroll
;               for (int jj = 0; jj < 4; ++jj) if (4 * j4 + jj < i) sacc -= l[jj] * x[4 * j4 + jj]; }
;           x[i] = sacc;
;           if ((i & 1) == 1) asm volatile("" : "+v"(loff) : "v"(sacc)); }
.LBB0_1107:
	s_movk_i32 s4, 0x480
	s_waitcnt lgkmcnt(0)
	v_mul_lo_u32 v1, v32, s4
	v_lshl_add_u32 v2, v1, 2, s3
	ds_read_b128 v[2:5], v2 offset:6288
	v_cmp_eq_u32_e32 vcc, 1, v152
	v_cndmask_b32_e64 v0, 0, 1.0, s[8:9]
	v_readlane_b32 s4, v238, 18
	v_cndmask_b32_e64 v6, 0, 1.0, vcc
	v_cmp_eq_u32_e32 vcc, 2, v152
	s_waitcnt lgkmcnt(0)
	v_fma_f32 v2, -v0, v2, v6
	v_readlane_b32 s5, v238, 19
	v_cndmask_b32_e64 v3, 0, 1.0, vcc
	v_cmp_eq_u32_e32 vcc, 3, v152
	v_lshl_add_u32 v8, v1, 2, s3
	ds_read_b128 v[4:7], v8 offset:6432
	v_cndmask_b32_e64 v10, 0, 1.0, vcc
	v_cmp_eq_u32_e32 vcc, 6, v152
	s_waitcnt lgkmcnt(0)
	ds_read_b128 v[6:9], v8 offset:6576
	v_lshlrev_b32_e32 v34, 1, v34
	v_cndmask_b32_e64 v20, 0, 1.0, vcc
	v_cmp_eq_u32_e32 vcc, 7, v152
	v_fma_f32 v3, -v0, v4, v3
	v_fma_f32 v3, -v5, v2, v3
	v_cndmask_b32_e64 v21, 0, 1.0, vcc
	v_cmp_eq_u32_e32 vcc, 8, v152
	s_waitcnt lgkmcnt(0)
	v_mov_b32_e32 v4, v7
	v_mov_b32_e32 v5, v8
	v_cndmask_b32_e64 v25, 0, 1.0, vcc
	v_cmp_eq_u32_e32 vcc, 9, v152
	v_fma_f32 v6, -v0, v6, v10
	v_pk_mul_f32 v[4:5], v[2:3], v[4:5]
	v_cndmask_b32_e64 v24, 0, 1.0, vcc
	v_cmp_eq_u32_e32 vcc, 10, v152
	v_sub_f32_e32 v4, v6, v4
	v_sub_f32_e32 v4, v4, v5
	v_cndmask_b32_e64 v50, 0, 1.0, vcc
	v_cmp_eq_u32_e32 vcc, 11, v152
	v_mov_b32_e32 v26, v3
	v_lshl_add_u32 v5, v1, 2, s3
	v_cndmask_b32_e64 v51, 0, 1.0, vcc
	v_cmp_eq_u32_e32 vcc, 12, v152
	ds_read_b128 v[6:9], v5 offset:6720
	ds_read_b128 v[10:13], v5 offset:6864
	v_cndmask_b32_e64 v23, 0, 1.0, vcc
	v_cmp_eq_u32_e32 vcc, 13, v152
	ds_read_b128 v[14:17], v5 offset:6880
	s_waitcnt lgkmcnt(0)
	v_mov_b32_e32 v17, v6
	v_cndmask_b32_e64 v22, 0, 1.0, vcc
	v_cmp_eq_u32_e32 vcc, 14, v152
	v_mov_b32_e32 v16, v10
	v_mov_b32_e32 v6, v11
	v_cndmask_b32_e64 v66, 0, 1.0, vcc
	v_cmp_eq_u32_e32 vcc, 15, v152
	v_mov_b32_e32 v10, v12
	v_mov_b32_e32 v11, v8
	v_cndmask_b32_e64 v67, 0, 1.0, vcc
	v_cmp_eq_u32_e32 vcc, 18, v152
	v_mov_b32_e32 v8, v13
	v_mov_b32_e32 v46, v3
	v_cndmask_b32_e64 v39, 0, 1.0, vcc
	v_cmp_eq_u32_e32 vcc, 19, v152
	v_mov_b32_e32 v47, v4
	s_cmpk_eq_i32 s78, 0x100
	v_cndmask_b32_e64 v37, 0, 1.0, vcc
	v_cmp_eq_u32_e32 vcc, 22, v152
	s_nop 1
	v_cndmask_b32_e64 v35, 0, 1.0, vcc
	v_cmp_eq_u32_e32 vcc, 23, v152
	s_nop 1
	v_cndmask_b32_e64 v33, 0, 1.0, vcc
	v_cmp_eq_u32_e32 vcc, 4, v152
	s_nop 1
	v_cndmask_b32_e64 v19, 0, 1.0, vcc
	v_cmp_eq_u32_e32 vcc, 5, v152
	s_nop 1
	v_cndmask_b32_e64 v18, 0, 1.0, vcc
	v_pk_fma_f32 v[16:17], v[0:1], v[16:17], v[18:19] op_sel_hi:[0,1,1] neg_lo:[1,0,0] neg_hi:[1,0,0]
	v_pk_fma_f32 v[6:7], v[2:3], v[6:7], v[16:17] op_sel_hi:[0,1,1] neg_lo:[1,0,0] neg_hi:[1,0,0]
	v_pk_fma_f32 v[6:7], v[26:27], v[10:11], v[6:7] op_sel_hi:[0,1,1] neg_lo:[1,0,0] neg_hi:[1,0,0]
	v_pk_fma_f32 v[6:7], v[8:9], v[4:5], v[6:7] op_sel_hi:[1,0,1] neg_lo:[1,0,0] neg_hi:[1,0,0]
	v_cmp_eq_u32_e32 vcc, 26, v152
	v_fma_f32 v9, -v14, v7, v6
	v_mov_b32_e32 v36, v9
	v_lshl_add_u32 v5, v1, 2, s3
	ds_read_b128 v[10:13], v5 offset:7008
	ds_read_b64 v[14:15], v5 offset:7024
	v_cndmask_b32_e64 v27, 0, 1.0, vcc
	v_cmp_eq_u32_e32 vcc, 16, v152
	s_waitcnt lgkmcnt(1)
	v_fma_f32 v8, -v0, v10, v20
	v_fma_f32 v8, -v2, v11, v8
	v_pk_mul_f32 v[10:11], v[46:47], v[12:13]
	v_cndmask_b32_e64 v41, 0, 1.0, vcc
	v_sub_f32_e32 v8, v8, v10
	v_sub_f32_e32 v16, v8, v11
	ds_read_b128 v[10:13], v5 offset:7152
	v_mov_b32_e32 v8, v7
	s_waitcnt lgkmcnt(1)
	v_pk_mul_f32 v[18:19], v[14:15], v[8:9]
	v_cmp_eq_u32_e32 vcc, 17, v152
	v_sub_f32_e32 v18, v16, v18
	ds_read_b128 v[14:17], v5 offset:7168
	s_waitcnt lgkmcnt(1)
	v_fma_f32 v5, -v0, v10, v21
	v_mov_b32_e32 v10, v11
	v_mov_b32_e32 v11, v12
	v_pk_mul_f32 v[10:11], v[2:3], v[10:11]
	v_cndmask_b32_e64 v40, 0, 1.0, vcc
	v_sub_f32_e32 v5, v5, v10
	v_sub_f32_e32 v12, v5, v11
	v_mov_b32_e32 v5, v7
	s_waitcnt lgkmcnt(0)
	v_pk_mov_b32 v[10:11], v[12:13], v[14:15] op_sel:[1,0]
	v_mov_b32_e32 v13, v16
	v_pk_mul_f32 v[10:11], v[4:5], v[10:11]
	v_cmp_eq_u32_e32 vcc, 20, v152
	v_sub_f32_e32 v10, v12, v10
	v_sub_f32_e32 v14, v10, v11
	v_sub_f32_e32 v11, v18, v19
	v_mov_b32_e32 v12, v15
	v_mov_b32_e32 v10, v9
	v_pk_mul_f32 v[12:13], v[12:13], v[10:11]
	v_mov_b32_e32 v38, v11
	v_sub_f32_e32 v12, v14, v12
	v_sub_f32_e32 v12, v12, v13
	s_nop 0
	v_lshl_add_u32 v13, v1, 2, s3
	ds_read_b128 v[14:17], v13 offset:7296
	ds_read_b128 v[18:21], v13 offset:7440
	ds_read_b128 v[28:31], v13 offset:7312
	ds_read_b128 v[42:45], v13 offset:7456
	s_waitcnt lgkmcnt(3)
	v_mov_b32_e32 v49, v14
	s_waitcnt lgkmcnt(2)
	v_mov_b32_e32 v48, v18
	v_pk_fma_f32 v[24:25], v[0:1], v[48:49], v[24:25] op_sel_hi:[0,1,1] neg_lo:[1,0,0] neg_hi:[1,0,0]
	v_mov_b32_e32 v14, v19
	v_pk_fma_f32 v[14:15], v[2:3], v[14:15], v[24:25] op_sel_hi:[0,1,1] neg_lo:[1,0,0] neg_hi:[1,0,0]
	v_mov_b32_e32 v18, v20
	v_mov_b32_e32 v19, v16
	v_pk_fma_f32 v[14:15], v[26:27], v[18:19], v[14:15] op_sel_hi:[0,1,1] neg_lo:[1,0,0] neg_hi:[1,0,0]
	v_mov_b32_e32 v16, v21
	v_pk_fma_f32 v[14:15], v[4:5], v[16:17], v[14:15] op_sel_hi:[0,1,1] neg_lo:[1,0,0] neg_hi:[1,0,0]
	s_waitcnt lgkmcnt(0)
	v_mov_b32_e32 v16, v42
	v_mov_b32_e32 v17, v28
	v_pk_fma_f32 v[14:15], v[6:7], v[16:17], v[14:15] op_sel:[1,0,0] neg_lo:[1,0,0] neg_hi:[1,0,0]
	ds_read_b128 v[16:19], v13 offset:7472
	v_mov_b32_e32 v28, v43
	v_pk_fma_f32 v[14:15], v[36:37], v[28:29], v[14:15] op_sel_hi:[0,1,1] neg_lo:[1,0,0] neg_hi:[1,0,0]
	v_mov_b32_e32 v20, v44
	v_mov_b32_e32 v21, v30
	v_pk_fma_f32 v[14:15], v[38:39], v[20:21], v[14:15] op_sel_hi:[0,1,1] neg_lo:[1,0,0] neg_hi:[1,0,0]
	v_mov_b32_e32 v30, v45
	v_pk_fma_f32 v[14:15], v[30:31], v[12:13], v[14:15] op_sel_hi:[1,0,1] neg_lo:[1,0,0] neg_hi:[1,0,0]
	v_cndmask_b32_e64 v49, 0, 1.0, vcc
	s_waitcnt lgkmcnt(0)
; #define LAS __attribute__((address_space(3)))
; __device__ __forceinline__ void delta_prep_wave(const Params& P, LAS unsigned char* lds, int idx, int wave, int lane) {
;     ...
;     { int loff = hh * 1152;
;       float x[32];
; #pragma unroll
;       for (int i = 0; i < 32; ++i) { float sacc = (i == n) ? 1.f : 0.f;
;           const LAS float* Lb = Lm + loff;
; #pragma unroll
;           for (int j4 = 0; j4 < (i + 3) / 4; ++j4) { const f32x4 l = *(const LAS f32x4*)(Lb + i * 36 + 4 * j4);
; #pragma unroll
;               for (int jj = 0; jj < 4; ++jj) if (4 * j4 + jj < i) sacc -= l[jj] * x[4 * j4 + jj]; }
;           x[i] = sacc;
;           if ((i & 1) == 1) asm volatile("" : "+v"(loff) : "v"(sacc)); }
	v_fma_f32 v17, -v16, v15, v14
	v_mov_b32_e32 v13, v15
	v_lshl_add_u32 v42, v1, 2, s3
	ds_read_b128 v[18:21], v42 offset:7584
	ds_read_b128 v[28:31], v42 offset:7600
	ds_read_b64 v[24:25], v42 offset:7616
	v_cmp_eq_u32_e32 vcc, 21, v152
	s_waitcnt lgkmcnt(2)
	v_fma_f32 v16, -v0, v18, v50
	v_fma_f32 v16, -v2, v19, v16
	v_pk_mul_f32 v[18:19], v[46:47], v[20:21]
	v_cndmask_b32_e64 v48, 0, 1.0, vcc
	v_sub_f32_e32 v16, v16, v18
	v_sub_f32_e32 v16, v16, v19
	s_waitcnt lgkmcnt(1)
	v_pk_mul_f32 v[18:19], v[8:9], v[28:29]
	v_cmp_eq_u32_e32 vcc, 27, v152
	v_sub_f32_e32 v8, v16, v18
	v_sub_f32_e32 v8, v8, v19
	v_mov_b32_e32 v18, v11
	v_mov_b32_e32 v19, v12
	v_pk_mul_f32 v[28:29], v[18:19], v[30:31]
	ds_read_b128 v[18:21], v42 offset:7728
	v_sub_f32_e32 v8, v8, v28
	v_sub_f32_e32 v8, v8, v29
	ds_read_b128 v[28:31], v42 offset:7744
	v_mov_b32_e32 v16, v15
	s_waitcnt lgkmcnt(2)
	v_pk_mul_f32 v[24:25], v[24:25], v[16:17]
	s_waitcnt lgkmcnt(1)
	v_fma_f32 v16, -v0, v18, v51
	v_mov_b32_e32 v18, v19
	v_mov_b32_e32 v19, v20
	v_pk_mul_f32 v[18:19], v[2:3], v[18:19]
	ds_read_b128 v[42:45], v42 offset:7760
	v_sub_f32_e32 v16, v16, v18
	v_sub_f32_e32 v16, v16, v19
	s_waitcnt lgkmcnt(1)
	v_pk_mov_b32 v[18:19], v[20:21], v[28:29] op_sel:[1,0]
	v_sub_f32_e32 v8, v8, v24
	v_pk_mul_f32 v[18:19], v[4:5], v[18:19]
	s_waitcnt lgkmcnt(0)
	v_mov_b32_e32 v20, v43
	v_sub_f32_e32 v16, v16, v18
	v_sub_f32_e32 v16, v16, v19
	v_mov_b32_e32 v18, v29
	v_mov_b32_e32 v19, v30
	v_pk_mul_f32 v[18:19], v[10:11], v[18:19]
	v_mov_b32_e32 v21, v44
	v_sub_f32_e32 v16, v16, v18
	v_sub_f32_e32 v16, v16, v19
	v_pk_mov_b32 v[18:19], v[30:31], v[42:43] op_sel:[1,0]
	s_nop 0
	v_pk_mul_f32 v[18:19], v[12:13], v[18:19]
	s_nop 0
	v_sub_f32_e32 v16, v16, v18
	v_sub_f32_e32 v16, v16, v19
	v_sub_f32_e32 v19, v8, v25
	v_mov_b32_e32 v18, v17
	v_pk_mul_f32 v[20:21], v[20:21], v[18:19]
	s_nop 0
	v_sub_f32_e32 v8, v16, v20
	v_sub_f32_e32 v20, v8, v21
	v_mov_b32_e32 v8, v17
	v_lshl_add_u32 v16, v1, 2, s3
	ds_read_b128 v[28:31], v16 offset:7904
	ds_read_b128 v[42:45], v16 offset:8016
	ds_read_b128 v[50:53], v16 offset:7872
	ds_read_b128 v[54:57], v16 offset:7888
	ds_read_b128 v[58:61], v16 offset:8032
	ds_read_b128 v[62:65], v16 offset:8048
	s_waitcnt lgkmcnt(4)
	v_mov_b32_e32 v24, v42
	s_waitcnt lgkmcnt(3)
	v_mov_b32_e32 v25, v50
	v_pk_fma_f32 v[22:23], v[0:1], v[24:25], v[22:23] op_sel_hi:[0,1,1] neg_lo:[1,0,0] neg_hi:[1,0,0]
	v_mov_b32_e32 v50, v43
	v_pk_fma_f32 v[22:23], v[2:3], v[50:51], v[22:23] op_sel_hi:[0,1,1] neg_lo:[1,0,0] neg_hi:[1,0,0]
	v_mov_b32_e32 v24, v44
	v_mov_b32_e32 v25, v52
	v_pk_fma_f32 v[22:23], v[26:27], v[24:25], v[22:23] op_sel_hi:[0,1,1] neg_lo:[1,0,0] neg_hi:[1,0,0]
	v_mov_b32_e32 v52, v45
	v_pk_fma_f32 v[22:23], v[4:5], v[52:53], v[22:23] op_sel_hi:[0,1,1] neg_lo:[1,0,0] neg_hi:[1,0,0]
	s_waitcnt lgkmcnt(1)
	v_mov_b32_e32 v24, v58
	v_mov_b32_e32 v25, v54
	v_pk_fma_f32 v[22:23], v[6:7], v[24:25], v[22:23] op_sel:[1,0,0] neg_lo:[1,0,0] neg_hi:[1,0,0]
	v_mov_b32_e32 v54, v59
	v_pk_fma_f32 v[22:23], v[36:37], v[54:55], v[22:23] op_sel_hi:[0,1,1] neg_lo:[1,0,0] neg_hi:[1,0,0]
	v_mov_b32_e32 v24, v60
	v_mov_b32_e32 v25, v56
	v_pk_fma_f32 v[22:23], v[38:39], v[24:25], v[22:23] op_sel_hi:[0,1,1] neg_lo:[1,0,0] neg_hi:[1,0,0]
	v_mov_b32_e32 v56, v61
	v_pk_fma_f32 v[22:23], v[12:13], v[56:57], v[22:23] op_sel_hi:[0,1,1] neg_lo:[1,0,0] neg_hi:[1,0,0]
	s_waitcnt lgkmcnt(0)
	v_mov_b32_e32 v24, v62
	v_mov_b32_e32 v25, v28
	ds_read_b128 v[42:45], v16 offset:8064
	v_pk_fma_f32 v[22:23], v[14:15], v[24:25], v[22:23] op_sel:[1,0,0] neg_lo:[1,0,0] neg_hi:[1,0,0]
	v_mov_b32_e32 v28, v63
	v_pk_fma_f32 v[22:23], v[8:9], v[28:29], v[22:23] op_sel_hi:[0,1,1] neg_lo:[1,0,0] neg_hi:[1,0,0]
	v_mov_b32_e32 v24, v64
	v_mov_b32_e32 v25, v30
	v_mov_b32_e32 v16, v19
	v_pk_fma_f32 v[22:23], v[16:17], v[24:25], v[22:23] op_sel_hi:[0,1,1] neg_lo:[1,0,0] neg_hi:[1,0,0]
	v_mov_b32_e32 v30, v65
	v_pk_fma_f32 v[22:23], v[30:31], v[20:21], v[22:23] op_sel_hi:[1,0,1] neg_lo:[1,0,0] neg_hi:[1,0,0]
	s_waitcnt lgkmcnt(0)
	v_fma_f32 v25, -v42, v23, v22
	v_mov_b32_e32 v21, v23
	v_lshl_add_u32 v54, v1, 2, s3
	ds_read_b128 v[28:31], v54 offset:8160
	ds_read_b128 v[42:45], v54 offset:8176
	ds_read_b128 v[50:53], v54 offset:8192
	ds_read_b64 v[46:47], v54 offset:8208
	s_waitcnt lgkmcnt(3)
	v_fma_f32 v24, -v0, v28, v66
	v_fma_f32 v24, -v2, v29, v24
	s_waitcnt lgkmcnt(2)
	v_pk_mov_b32 v[28:29], v[30:31], v[42:43] op_sel:[1,0]
	v_fma_f32 v24, -v3, v30, v24
	v_pk_mul_f32 v[28:29], v[4:5], v[28:29]
	s_nop 0
	v_sub_f32_e32 v24, v24, v28
	v_sub_f32_e32 v24, v24, v29
	v_mov_b32_e32 v28, v43
	v_mov_b32_e32 v29, v44
	v_pk_mul_f32 v[28:29], v[10:11], v[28:29]
	s_nop 0
	v_sub_f32_e32 v24, v24, v28
	v_sub_f32_e32 v24, v24, v29
	s_waitcnt lgkmcnt(1)
	v_pk_mov_b32 v[28:29], v[44:45], v[50:51] op_sel:[1,0]
	ds_read_b128 v[42:45], v54 offset:8320
	v_pk_mul_f32 v[28:29], v[12:13], v[28:29]
	s_nop 0
	v_sub_f32_e32 v24, v24, v28
	v_sub_f32_e32 v24, v24, v29
	v_mov_b32_e32 v28, v19
	v_mov_b32_e32 v29, v20
	v_fma_f32 v24, -v17, v51, v24
	v_pk_mul_f32 v[28:29], v[28:29], v[52:53]
	s_nop 0
	v_sub_f32_e32 v24, v24, v28
	v_sub_f32_e32 v50, v24, v29
	ds_read_b128 v[28:31], v54 offset:8304
	v_mov_b32_e32 v24, v23
	s_waitcnt lgkmcnt(2)
	v_pk_mul_f32 v[46:47], v[46:47], v[24:25]
	s_waitcnt lgkmcnt(0)
	v_fma_f32 v28, -v0, v28, v67
	v_fma_f32 v28, -v2, v29, v28
	v_fma_f32 v30, -v3, v30, v28
	v_pk_mov_b32 v[28:29], v[30:31], v[42:43] op_sel:[1,0]
	v_mov_b32_e32 v42, v43
	v_pk_mul_f32 v[28:29], v[4:5], v[28:29]
	v_mov_b32_e32 v43, v44
	v_sub_f32_e32 v5, v30, v28
	v_sub_f32_e32 v5, v5, v29
	ds_read_b128 v[28:31], v54 offset:8336
	v_pk_mul_f32 v[42:43], v[10:11], v[42:43]
	v_sub_f32_e32 v24, v50, v46
	v_sub_f32_e32 v5, v5, v42
	v_sub_f32_e32 v5, v5, v43
	ds_read_b128 v[50:53], v54 offset:8352
	s_waitcnt lgkmcnt(1)
; #define LAS __attribute__((address_space(3)))
; __device__ __forceinline__ void delta_prep_wave(const Params& P, LAS unsigned char* lds, int idx, int wave, int lane) {
;     ...
;     { int loff = hh * 1152;
;       float x[32];
; #pragma unroll
;       for (int i = 0; i < 32; ++i) { float sacc = (i == n) ? 1.f : 0.f;
;           const LAS float* Lb = Lm + loff;
; #pragma unroll
;           for (int j4 = 0; j4 < (i + 3) / 4; ++j4) { const f32x4 l = *(const LAS f32x4*)(Lb + i * 36 + 4 * j4);
; #pragma unroll
;               for (int jj = 0; jj < 4; ++jj) if (4 * j4 + jj < i) sacc -= l[jj] * x[4 * j4 + jj]; }
;           x[i] = sacc;
;           if ((i & 1) == 1) asm volatile("" : "+v"(loff) : "v"(sacc)); }
	v_pk_mov_b32 v[42:43], v[44:45], v[28:29] op_sel:[1,0]
	v_mov_b32_e32 v28, v29
	v_pk_mul_f32 v[42:43], v[12:13], v[42:43]
	v_mov_b32_e32 v29, v30
	v_sub_f32_e32 v5, v5, v42
	v_sub_f32_e32 v5, v5, v43
	v_pk_mul_f32 v[28:29], v[18:19], v[28:29]
	v_mov_b32_e32 v10, v25
	v_sub_f32_e32 v5, v5, v28
	v_sub_f32_e32 v5, v5, v29
	s_waitcnt lgkmcnt(0)
	v_pk_mov_b32 v[28:29], v[30:31], v[50:51] op_sel:[1,0]
	v_mov_b32_e32 v30, v51
	v_pk_mul_f32 v[28:29], v[20:21], v[28:29]
	v_mov_b32_e32 v31, v52
	v_sub_f32_e32 v5, v5, v28
	v_sub_f32_e32 v5, v5, v29
	v_sub_f32_e32 v29, v24, v47
	v_mov_b32_e32 v28, v25
	v_pk_mul_f32 v[30:31], v[30:31], v[28:29]
	v_mov_b32_e32 v24, v29
	v_sub_f32_e32 v5, v5, v30
	v_sub_f32_e32 v30, v5, v31
	s_nop 0
	v_lshl_add_u32 v5, v1, 2, s3
	ds_read_b128 v[42:45], v5 offset:8592
	ds_read_b128 v[50:53], v5 offset:8448
	ds_read_b128 v[54:57], v5 offset:8464
	ds_read_b128 v[58:61], v5 offset:8480
	ds_read_b128 v[62:65], v5 offset:8496
	ds_read_b128 v[66:69], v5 offset:8608
	s_waitcnt lgkmcnt(5)
	v_mov_b32_e32 v46, v42
	s_waitcnt lgkmcnt(4)
	v_mov_b32_e32 v47, v50
	v_pk_fma_f32 v[40:41], v[0:1], v[46:47], v[40:41] op_sel_hi:[0,1,1] neg_lo:[1,0,0] neg_hi:[1,0,0]
	v_mov_b32_e32 v50, v43
	v_pk_fma_f32 v[40:41], v[2:3], v[50:51], v[40:41] op_sel_hi:[0,1,1] neg_lo:[1,0,0] neg_hi:[1,0,0]
	v_mov_b32_e32 v42, v44
	v_mov_b32_e32 v43, v52
	v_pk_fma_f32 v[40:41], v[26:27], v[42:43], v[40:41] op_sel_hi:[0,1,1] neg_lo:[1,0,0] neg_hi:[1,0,0]
	v_mov_b32_e32 v52, v45
	v_pk_fma_f32 v[50:51], v[4:5], v[52:53], v[40:41] op_sel_hi:[0,1,1] neg_lo:[1,0,0] neg_hi:[1,0,0]
	s_waitcnt lgkmcnt(0)
	v_mov_b32_e32 v52, v66
	v_mov_b32_e32 v53, v54
	ds_read_b128 v[40:43], v5 offset:8624
	ds_read_b128 v[44:47], v5 offset:8640
	v_pk_fma_f32 v[50:51], v[6:7], v[52:53], v[50:51] op_sel:[1,0,0] neg_lo:[1,0,0] neg_hi:[1,0,0]
	v_mov_b32_e32 v54, v67
	v_pk_fma_f32 v[50:51], v[36:37], v[54:55], v[50:51] op_sel_hi:[0,1,1] neg_lo:[1,0,0] neg_hi:[1,0,0]
	v_mov_b32_e32 v52, v68
	v_mov_b32_e32 v53, v56
	v_pk_fma_f32 v[50:51], v[38:39], v[52:53], v[50:51] op_sel_hi:[0,1,1] neg_lo:[1,0,0] neg_hi:[1,0,0]
	v_mov_b32_e32 v56, v69
	v_pk_fma_f32 v[50:51], v[12:13], v[56:57], v[50:51] op_sel_hi:[0,1,1] neg_lo:[1,0,0] neg_hi:[1,0,0]
	s_waitcnt lgkmcnt(1)
	v_mov_b32_e32 v52, v40
	v_mov_b32_e32 v53, v58
	v_pk_fma_f32 v[50:51], v[14:15], v[52:53], v[50:51] op_sel:[1,0,0] neg_lo:[1,0,0] neg_hi:[1,0,0]
	v_mov_b32_e32 v58, v41
	v_pk_fma_f32 v[40:41], v[8:9], v[58:59], v[50:51] op_sel_hi:[0,1,1] neg_lo:[1,0,0] neg_hi:[1,0,0]
	v_mov_b32_e32 v50, v42
	v_mov_b32_e32 v51, v60
	v_pk_fma_f32 v[40:41], v[16:17], v[50:51], v[40:41] op_sel_hi:[0,1,1] neg_lo:[1,0,0] neg_hi:[1,0,0]
	v_mov_b32_e32 v60, v43
	v_pk_fma_f32 v[40:41], v[20:21], v[60:61], v[40:41] op_sel_hi:[0,1,1] neg_lo:[1,0,0] neg_hi:[1,0,0]
	s_waitcnt lgkmcnt(0)
	v_mov_b32_e32 v42, v44
	v_mov_b32_e32 v43, v62
	v_pk_fma_f32 v[40:41], v[22:23], v[42:43], v[40:41] op_sel:[1,0,0] neg_lo:[1,0,0] neg_hi:[1,0,0]
	v_mov_b32_e32 v62, v45
	ds_read_b128 v[42:45], v5 offset:8656
	v_pk_fma_f32 v[40:41], v[10:11], v[62:63], v[40:41] op_sel_hi:[0,1,1] neg_lo:[1,0,0] neg_hi:[1,0,0]
	v_mov_b32_e32 v50, v46
	v_mov_b32_e32 v51, v64
	v_pk_fma_f32 v[40:41], v[24:25], v[50:51], v[40:41] op_sel_hi:[0,1,1] neg_lo:[1,0,0] neg_hi:[1,0,0]
	v_mov_b32_e32 v64, v47
	v_pk_fma_f32 v[40:41], v[64:65], v[30:31], v[40:41] op_sel_hi:[1,0,1] neg_lo:[1,0,0] neg_hi:[1,0,0]
	s_waitcnt lgkmcnt(0)
	v_fma_f32 v43, -v42, v41, v40
	v_mov_b32_e32 v42, v41
	v_lshl_add_u32 v5, v1, 2, s3
	ds_read_b128 v[44:47], v5 offset:8736
	ds_read_b128 v[50:53], v5 offset:8752
	ds_read_b128 v[54:57], v5 offset:8768
	ds_read_b128 v[58:61], v5 offset:8784
	v_mov_b32_e32 v31, v41
	s_waitcnt lgkmcnt(3)
	v_fma_f32 v39, -v0, v44, v39
	v_fma_f32 v39, -v2, v45, v39
	v_fma_f32 v39, -v3, v46, v39
	v_fma_f32 v39, -v4, v47, v39
	s_waitcnt lgkmcnt(2)
	v_fma_f32 v39, -v7, v50, v39
	v_fma_f32 v39, -v9, v51, v39
	s_waitcnt lgkmcnt(1)
	v_pk_mov_b32 v[44:45], v[52:53], v[54:55] op_sel:[1,0]
	v_fma_f32 v39, -v11, v52, v39
	v_pk_mul_f32 v[44:45], v[12:13], v[44:45]
	ds_read_b64 v[52:53], v5 offset:8800
	v_sub_f32_e32 v39, v39, v44
	v_sub_f32_e32 v39, v39, v45
	v_mov_b32_e32 v44, v55
	v_mov_b32_e32 v45, v56
	v_pk_mul_f32 v[44:45], v[18:19], v[44:45]
	s_nop 0
	v_sub_f32_e32 v39, v39, v44
	v_sub_f32_e32 v39, v39, v45
	s_waitcnt lgkmcnt(1)
	v_pk_mov_b32 v[44:45], v[56:57], v[58:59] op_sel:[1,0]
	ds_read_b128 v[54:57], v5 offset:8912
	v_pk_mul_f32 v[44:45], v[20:21], v[44:45]
	s_nop 0
	v_sub_f32_e32 v39, v39, v44
	v_sub_f32_e32 v39, v39, v45
	v_mov_b32_e32 v44, v29
	v_mov_b32_e32 v45, v30
	v_pk_mul_f32 v[50:51], v[44:45], v[60:61]
	ds_read_b128 v[44:47], v5 offset:8880
	v_fma_f32 v39, -v25, v59, v39
	v_sub_f32_e32 v39, v39, v50
	v_sub_f32_e32 v39, v39, v51
	s_waitcnt lgkmcnt(2)
	v_pk_mul_f32 v[58:59], v[52:53], v[42:43]
	ds_read_b128 v[50:53], v5 offset:8896
	s_waitcnt lgkmcnt(1)
	v_fma_f32 v37, -v0, v44, v37
	v_fma_f32 v37, -v2, v45, v37
	v_fma_f32 v37, -v3, v46, v37
	v_fma_f32 v37, -v4, v47, v37
	s_waitcnt lgkmcnt(0)
	v_fma_f32 v37, -v7, v50, v37
	v_fma_f32 v37, -v9, v51, v37
	v_pk_mov_b32 v[44:45], v[52:53], v[54:55] op_sel:[1,0]
	v_fma_f32 v37, -v11, v52, v37
	v_pk_mul_f32 v[44:45], v[12:13], v[44:45]
	v_mov_b32_e32 v50, v55
	v_sub_f32_e32 v13, v37, v44
	v_sub_f32_e32 v13, v13, v45
	ds_read_b128 v[44:47], v5 offset:8928
	v_mov_b32_e32 v51, v56
	v_pk_mul_f32 v[50:51], v[18:19], v[50:51]
	v_sub_f32_e32 v39, v39, v58
	v_sub_f32_e32 v13, v13, v50
	v_sub_f32_e32 v13, v13, v51
	ds_read_b128 v[50:53], v5 offset:8944
	s_waitcnt lgkmcnt(1)
; #define LAS __attribute__((address_space(3)))
; __device__ __forceinline__ void delta_prep_wave(const Params& P, LAS unsigned char* lds, int idx, int wave, int lane) {
;     ...
;     { int loff = hh * 1152;
;       float x[32];
; #pragma unroll
;       for (int i = 0; i < 32; ++i) { float sacc = (i == n) ? 1.f : 0.f;
;           const LAS float* Lb = Lm + loff;
; #pragma unroll
;           for (int j4 = 0; j4 < (i + 3) / 4; ++j4) { const f32x4 l = *(const LAS f32x4*)(Lb + i * 36 + 4 * j4);
; #pragma unroll
;               for (int jj = 0; jj < 4; ++jj) if (4 * j4 + jj < i) sacc -= l[jj] * x[4 * j4 + jj]; }
;           x[i] = sacc;
;           if ((i & 1) == 1) asm volatile("" : "+v"(loff) : "v"(sacc)); }
	v_pk_mov_b32 v[54:55], v[56:57], v[44:45] op_sel:[1,0]
	v_mov_b32_e32 v44, v45
	v_pk_mul_f32 v[54:55], v[20:21], v[54:55]
	v_mov_b32_e32 v45, v46
	v_sub_f32_e32 v5, v13, v54
	v_sub_f32_e32 v5, v5, v55
	v_pk_mul_f32 v[44:45], v[28:29], v[44:45]
	v_mov_b32_e32 v18, v43
	v_sub_f32_e32 v5, v5, v44
	v_sub_f32_e32 v5, v5, v45
	s_waitcnt lgkmcnt(0)
	v_pk_mov_b32 v[44:45], v[46:47], v[50:51] op_sel:[1,0]
	v_mov_b32_e32 v46, v51
	v_pk_mul_f32 v[44:45], v[30:31], v[44:45]
	v_mov_b32_e32 v47, v52
	v_sub_f32_e32 v5, v5, v44
	v_sub_f32_e32 v5, v5, v45
	v_sub_f32_e32 v45, v39, v59
	v_mov_b32_e32 v44, v43
	v_pk_mul_f32 v[46:47], v[46:47], v[44:45]
	v_mov_b32_e32 v42, v45
	v_sub_f32_e32 v5, v5, v46
	v_sub_f32_e32 v46, v5, v47
	s_nop 0
	v_lshl_add_u32 v5, v1, 2, s3
	ds_read_b128 v[50:53], v5 offset:9088
	ds_read_b128 v[54:57], v5 offset:9168
	ds_read_b128 v[58:61], v5 offset:9024
	ds_read_b128 v[62:65], v5 offset:9040
	ds_read_b128 v[66:69], v5 offset:9056
	ds_read_b128 v[70:73], v5 offset:9072
	ds_read_b128 v[74:77], v5 offset:9184
	s_waitcnt lgkmcnt(5)
	v_mov_b32_e32 v78, v54
	s_waitcnt lgkmcnt(4)
	v_mov_b32_e32 v79, v58
	v_pk_fma_f32 v[48:49], v[0:1], v[78:79], v[48:49] op_sel_hi:[0,1,1] neg_lo:[1,0,0] neg_hi:[1,0,0]
	v_mov_b32_e32 v58, v55
	v_pk_fma_f32 v[48:49], v[2:3], v[58:59], v[48:49] op_sel_hi:[0,1,1] neg_lo:[1,0,0] neg_hi:[1,0,0]
	v_mov_b32_e32 v54, v56
	v_mov_b32_e32 v55, v60
	v_pk_fma_f32 v[48:49], v[26:27], v[54:55], v[48:49] op_sel_hi:[0,1,1] neg_lo:[1,0,0] neg_hi:[1,0,0]
	v_mov_b32_e32 v60, v57
	ds_read_b128 v[54:57], v5 offset:9200
	v_pk_fma_f32 v[48:49], v[4:5], v[60:61], v[48:49] op_sel_hi:[0,1,1] neg_lo:[1,0,0] neg_hi:[1,0,0]
	s_waitcnt lgkmcnt(1)
	v_mov_b32_e32 v58, v74
	v_mov_b32_e32 v59, v62
	v_pk_fma_f32 v[48:49], v[6:7], v[58:59], v[48:49] op_sel:[1,0,0] neg_lo:[1,0,0] neg_hi:[1,0,0]
	v_mov_b32_e32 v62, v75
	v_pk_fma_f32 v[48:49], v[36:37], v[62:63], v[48:49] op_sel_hi:[0,1,1] neg_lo:[1,0,0] neg_hi:[1,0,0]
	v_mov_b32_e32 v58, v76
	v_mov_b32_e32 v59, v64
	v_pk_fma_f32 v[48:49], v[38:39], v[58:59], v[48:49] op_sel_hi:[0,1,1] neg_lo:[1,0,0] neg_hi:[1,0,0]
	v_mov_b32_e32 v64, v77
	v_pk_fma_f32 v[48:49], v[12:13], v[64:65], v[48:49] op_sel_hi:[0,1,1] neg_lo:[1,0,0] neg_hi:[1,0,0]
	s_waitcnt lgkmcnt(0)
	v_mov_b32_e32 v78, v54
	v_mov_b32_e32 v79, v66
	ds_read_b128 v[58:61], v5 offset:9216
	ds_read_b128 v[62:65], v5 offset:9232
	ds_read_b128 v[74:77], v5 offset:9248
	v_pk_fma_f32 v[48:49], v[14:15], v[78:79], v[48:49] op_sel:[1,0,0] neg_lo:[1,0,0] neg_hi:[1,0,0]
	v_mov_b32_e32 v66, v55
	v_pk_fma_f32 v[48:49], v[8:9], v[66:67], v[48:49] op_sel_hi:[0,1,1] neg_lo:[1,0,0] neg_hi:[1,0,0]
	v_mov_b32_e32 v54, v56
	v_mov_b32_e32 v55, v68
	v_pk_fma_f32 v[48:49], v[16:17], v[54:55], v[48:49] op_sel_hi:[0,1,1] neg_lo:[1,0,0] neg_hi:[1,0,0]
	v_mov_b32_e32 v68, v57
	v_pk_fma_f32 v[48:49], v[20:21], v[68:69], v[48:49] op_sel_hi:[0,1,1] neg_lo:[1,0,0] neg_hi:[1,0,0]
	s_waitcnt lgkmcnt(2)
	v_mov_b32_e32 v54, v58
	v_mov_b32_e32 v55, v70
	v_pk_fma_f32 v[48:49], v[22:23], v[54:55], v[48:49] op_sel:[1,0,0] neg_lo:[1,0,0] neg_hi:[1,0,0]
	v_mov_b32_e32 v70, v59
	v_pk_fma_f32 v[48:49], v[10:11], v[70:71], v[48:49] op_sel_hi:[0,1,1] neg_lo:[1,0,0] neg_hi:[1,0,0]
	v_mov_b32_e32 v54, v60
	v_mov_b32_e32 v55, v72
	v_pk_fma_f32 v[48:49], v[24:25], v[54:55], v[48:49] op_sel_hi:[0,1,1] neg_lo:[1,0,0] neg_hi:[1,0,0]
	v_mov_b32_e32 v72, v61
	v_pk_fma_f32 v[48:49], v[30:31], v[72:73], v[48:49] op_sel_hi:[0,1,1] neg_lo:[1,0,0] neg_hi:[1,0,0]
	s_waitcnt lgkmcnt(1)
	v_mov_b32_e32 v54, v62
	v_mov_b32_e32 v55, v50
	v_pk_fma_f32 v[48:49], v[40:41], v[54:55], v[48:49] op_sel:[1,0,0] neg_lo:[1,0,0] neg_hi:[1,0,0]
	v_mov_b32_e32 v50, v63
	v_pk_fma_f32 v[48:49], v[18:19], v[50:51], v[48:49] op_sel_hi:[0,1,1] neg_lo:[1,0,0] neg_hi:[1,0,0]
	v_mov_b32_e32 v50, v64
	v_mov_b32_e32 v51, v52
	v_pk_fma_f32 v[48:49], v[42:43], v[50:51], v[48:49] op_sel_hi:[0,1,1] neg_lo:[1,0,0] neg_hi:[1,0,0]
	v_mov_b32_e32 v52, v65
	v_pk_fma_f32 v[48:49], v[52:53], v[46:47], v[48:49] op_sel_hi:[1,0,1] neg_lo:[1,0,0] neg_hi:[1,0,0]
	v_cndmask_b32_e64 v13, 0, 1.0, vcc
	s_waitcnt lgkmcnt(0)
	v_fma_f32 v51, -v74, v49, v48
	v_mov_b32_e32 v50, v49
	v_lshl_add_u32 v5, v1, 2, s3
	ds_read_b128 v[52:55], v5 offset:9312
	ds_read_b128 v[56:59], v5 offset:9328
	ds_read_b128 v[60:63], v5 offset:9344
	ds_read_b128 v[64:67], v5 offset:9360
	v_mov_b32_e32 v47, v49
	v_cmp_eq_u32_e32 vcc, 24, v152
	s_waitcnt lgkmcnt(3)
	v_fma_f32 v35, -v0, v52, v35
	v_fma_f32 v35, -v2, v53, v35
	v_fma_f32 v35, -v3, v54, v35
	v_fma_f32 v35, -v4, v55, v35
	s_waitcnt lgkmcnt(2)
	v_fma_f32 v35, -v7, v56, v35
	v_fma_f32 v35, -v9, v57, v35
	v_fma_f32 v35, -v11, v58, v35
	v_fma_f32 v35, -v12, v59, v35
	s_waitcnt lgkmcnt(1)
	v_fma_f32 v35, -v15, v60, v35
	v_fma_f32 v35, -v17, v61, v35
	s_waitcnt lgkmcnt(0)
	v_pk_mov_b32 v[52:53], v[62:63], v[64:65] op_sel:[1,0]
	v_fma_f32 v35, -v19, v62, v35
	v_pk_mul_f32 v[52:53], v[20:21], v[52:53]
	v_mov_b32_e32 v56, v65
	v_sub_f32_e32 v35, v35, v52
	v_sub_f32_e32 v35, v35, v53
	ds_read_b128 v[52:55], v5 offset:9376
	ds_read_b64 v[58:59], v5 offset:9392
	v_mov_b32_e32 v57, v66
	v_pk_mul_f32 v[56:57], v[28:29], v[56:57]
	ds_read_b128 v[62:65], v5 offset:9504
	v_sub_f32_e32 v35, v35, v56
	v_sub_f32_e32 v35, v35, v57
	s_waitcnt lgkmcnt(2)
	v_pk_mov_b32 v[56:57], v[66:67], v[52:53] op_sel:[1,0]
	s_waitcnt lgkmcnt(1)
	v_pk_mul_f32 v[66:67], v[58:59], v[50:51]
	v_pk_mul_f32 v[56:57], v[30:31], v[56:57]
	ds_read_b128 v[58:61], v5 offset:9472
	v_sub_f32_e32 v35, v35, v56
	v_sub_f32_e32 v35, v35, v57
	v_mov_b32_e32 v56, v45
	v_mov_b32_e32 v57, v46
	v_fma_f32 v35, -v43, v53, v35
	v_pk_mul_f32 v[52:53], v[56:57], v[54:55]
	v_cndmask_b32_e64 v91, 0, 1.0, vcc
	v_sub_f32_e32 v35, v35, v52
	v_sub_f32_e32 v35, v35, v53
	ds_read_b128 v[52:55], v5 offset:9456
	v_sub_f32_e32 v35, v35, v66
	v_cmp_eq_u32_e32 vcc, 25, v152
	s_waitcnt lgkmcnt(0)
; #define LAS __attribute__((address_space(3)))
; __device__ __forceinline__ void delta_prep_wave(const Params& P, LAS unsigned char* lds, int idx, int wave, int lane) {
;     ...
;     { int loff = hh * 1152;
;       float x[32];
; #pragma unroll
;       for (int i = 0; i < 32; ++i) { float sacc = (i == n) ? 1.f : 0.f;
;           const LAS float* Lb = Lm + loff;
; #pragma unroll
;           for (int j4 = 0; j4 < (i + 3) / 4; ++j4) { const f32x4 l = *(const LAS f32x4*)(Lb + i * 36 + 4 * j4);
; #pragma unroll
;               for (int jj = 0; jj < 4; ++jj) if (4 * j4 + jj < i) sacc -= l[jj] * x[4 * j4 + jj]; }
;           x[i] = sacc;
;           if ((i & 1) == 1) asm volatile("" : "+v"(loff) : "v"(sacc)); }
	v_fma_f32 v33, -v0, v52, v33
	v_fma_f32 v33, -v2, v53, v33
	v_fma_f32 v33, -v3, v54, v33
	v_fma_f32 v33, -v4, v55, v33
	ds_read_b128 v[52:55], v5 offset:9488
	v_fma_f32 v33, -v7, v58, v33
	v_fma_f32 v33, -v9, v59, v33
	v_fma_f32 v33, -v11, v60, v33
	v_fma_f32 v33, -v12, v61, v33
	s_waitcnt lgkmcnt(0)
	v_fma_f32 v33, -v15, v52, v33
	v_fma_f32 v33, -v17, v53, v33
	v_pk_mov_b32 v[52:53], v[54:55], v[62:63] op_sel:[1,0]
	v_fma_f32 v33, -v19, v54, v33
	v_pk_mul_f32 v[52:53], v[20:21], v[52:53]
	v_mov_b32_e32 v58, v63
	v_sub_f32_e32 v21, v33, v52
	v_sub_f32_e32 v21, v21, v53
	ds_read_b128 v[52:55], v5 offset:9520
	v_mov_b32_e32 v59, v64
	v_pk_mul_f32 v[58:59], v[28:29], v[58:59]
	v_cndmask_b32_e64 v90, 0, 1.0, vcc
	v_sub_f32_e32 v21, v21, v58
	v_sub_f32_e32 v21, v21, v59
	ds_read_b128 v[58:61], v5 offset:9536
	s_waitcnt lgkmcnt(1)
	v_pk_mov_b32 v[62:63], v[64:65], v[52:53] op_sel:[1,0]
	v_mov_b32_e32 v52, v53
	v_pk_mul_f32 v[62:63], v[30:31], v[62:63]
	v_mov_b32_e32 v53, v54
	v_sub_f32_e32 v5, v21, v62
	v_sub_f32_e32 v5, v5, v63
	v_pk_mul_f32 v[52:53], v[44:45], v[52:53]
	v_cmp_eq_u32_e32 vcc, 30, v152
	v_sub_f32_e32 v5, v5, v52
	v_sub_f32_e32 v5, v5, v53
	s_waitcnt lgkmcnt(0)
	v_pk_mov_b32 v[52:53], v[54:55], v[58:59] op_sel:[1,0]
	v_mov_b32_e32 v54, v59
	v_pk_mul_f32 v[52:53], v[46:47], v[52:53]
	v_mov_b32_e32 v55, v60
	v_sub_f32_e32 v5, v5, v52
	v_sub_f32_e32 v5, v5, v53
	v_sub_f32_e32 v53, v35, v67
	v_mov_b32_e32 v52, v51
	v_pk_mul_f32 v[54:55], v[54:55], v[52:53]
	v_ashrrev_i32_e32 v33, 31, v32
	v_sub_f32_e32 v5, v5, v54
	v_sub_f32_e32 v54, v5, v55
	v_lshl_add_u64 v[32:33], s[6:7], 0, v[32:33]
	v_lshl_add_u32 v5, v1, 2, s3
	ds_read_b128 v[58:61], v5 offset:9600
	ds_read_b128 v[62:65], v5 offset:9616
	ds_read_b128 v[66:69], v5 offset:9632
	ds_read_b128 v[70:73], v5 offset:9648
	ds_read_b128 v[74:77], v5 offset:9664
	ds_read_b128 v[78:81], v5 offset:9680
	ds_read_b128 v[82:85], v5 offset:9744
	ds_read_b128 v[86:89], v5 offset:9760
	s_waitcnt lgkmcnt(7)
	v_mov_b32_e32 v93, v58
	v_lshlrev_b64 v[32:33], 11, v[32:33]
	v_lshl_add_u64 v[32:33], s[4:5], 0, v[32:33]
	s_waitcnt lgkmcnt(1)
	v_mov_b32_e32 v92, v82
	v_pk_fma_f32 v[94:95], v[0:1], v[92:93], v[90:91] op_sel_hi:[0,1,1] neg_lo:[1,0,0] neg_hi:[1,0,0]
	v_mov_b32_e32 v58, v83
	v_pk_fma_f32 v[58:59], v[2:3], v[58:59], v[94:95] op_sel_hi:[0,1,1] neg_lo:[1,0,0] neg_hi:[1,0,0]
	v_mov_b32_e32 v82, v84
	v_mov_b32_e32 v83, v60
	v_pk_fma_f32 v[58:59], v[26:27], v[82:83], v[58:59] op_sel_hi:[0,1,1] neg_lo:[1,0,0] neg_hi:[1,0,0]
	v_mov_b32_e32 v60, v85
	ds_read_b128 v[90:93], v5 offset:9776
	v_pk_fma_f32 v[58:59], v[4:5], v[60:61], v[58:59] op_sel_hi:[0,1,1] neg_lo:[1,0,0] neg_hi:[1,0,0]
	s_waitcnt lgkmcnt(1)
	v_mov_b32_e32 v60, v86
	v_mov_b32_e32 v61, v62
	v_pk_fma_f32 v[58:59], v[6:7], v[60:61], v[58:59] op_sel:[1,0,0] neg_lo:[1,0,0] neg_hi:[1,0,0]
	v_mov_b32_e32 v62, v87
	v_pk_fma_f32 v[58:59], v[36:37], v[62:63], v[58:59] op_sel_hi:[0,1,1] neg_lo:[1,0,0] neg_hi:[1,0,0]
	v_mov_b32_e32 v60, v88
	v_mov_b32_e32 v61, v64
	v_pk_fma_f32 v[58:59], v[38:39], v[60:61], v[58:59] op_sel_hi:[0,1,1] neg_lo:[1,0,0] neg_hi:[1,0,0]
	v_mov_b32_e32 v64, v89
	v_pk_fma_f32 v[62:63], v[12:13], v[64:65], v[58:59] op_sel_hi:[0,1,1] neg_lo:[1,0,0] neg_hi:[1,0,0]
	ds_read_b128 v[58:61], v5 offset:9792
	s_waitcnt lgkmcnt(1)
	v_mov_b32_e32 v64, v90
	v_mov_b32_e32 v65, v66
	v_pk_fma_f32 v[62:63], v[14:15], v[64:65], v[62:63] op_sel:[1,0,0] neg_lo:[1,0,0] neg_hi:[1,0,0]
	v_mov_b32_e32 v66, v91
	v_pk_fma_f32 v[62:63], v[8:9], v[66:67], v[62:63] op_sel_hi:[0,1,1] neg_lo:[1,0,0] neg_hi:[1,0,0]
	v_mov_b32_e32 v64, v92
	v_mov_b32_e32 v65, v68
	v_pk_fma_f32 v[62:63], v[16:17], v[64:65], v[62:63] op_sel_hi:[0,1,1] neg_lo:[1,0,0] neg_hi:[1,0,0]
	v_mov_b32_e32 v68, v93
	v_pk_fma_f32 v[86:87], v[20:21], v[68:69], v[62:63] op_sel_hi:[0,1,1] neg_lo:[1,0,0] neg_hi:[1,0,0]
	s_waitcnt lgkmcnt(0)
	v_mov_b32_e32 v88, v58
	v_mov_b32_e32 v89, v70
	ds_read_b128 v[62:65], v5 offset:9808
	ds_read_b128 v[66:69], v5 offset:9824
	ds_read_b128 v[82:85], v5 offset:9840
	s_waitcnt lgkmcnt(0)
	v_pk_fma_f32 v[84:85], v[22:23], v[88:89], v[86:87] op_sel:[1,0,0] neg_lo:[1,0,0] neg_hi:[1,0,0]
	v_mov_b32_e32 v70, v59
	v_pk_fma_f32 v[58:59], v[10:11], v[70:71], v[84:85] op_sel_hi:[0,1,1] neg_lo:[1,0,0] neg_hi:[1,0,0]
	v_mov_b32_e32 v70, v60
	v_mov_b32_e32 v71, v72
	v_pk_fma_f32 v[58:59], v[24:25], v[70:71], v[58:59] op_sel_hi:[0,1,1] neg_lo:[1,0,0] neg_hi:[1,0,0]
	v_mov_b32_e32 v72, v61
	v_pk_fma_f32 v[58:59], v[30:31], v[72:73], v[58:59] op_sel_hi:[0,1,1] neg_lo:[1,0,0] neg_hi:[1,0,0]
	v_mov_b32_e32 v60, v62
	v_mov_b32_e32 v61, v74
	v_pk_fma_f32 v[58:59], v[40:41], v[60:61], v[58:59] op_sel:[1,0,0] neg_lo:[1,0,0] neg_hi:[1,0,0]
	v_mov_b32_e32 v74, v63
	v_pk_fma_f32 v[58:59], v[18:19], v[74:75], v[58:59] op_sel_hi:[0,1,1] neg_lo:[1,0,0] neg_hi:[1,0,0]
	v_mov_b32_e32 v60, v64
	v_mov_b32_e32 v61, v76
	v_pk_fma_f32 v[58:59], v[42:43], v[60:61], v[58:59] op_sel_hi:[0,1,1] neg_lo:[1,0,0] neg_hi:[1,0,0]
	v_mov_b32_e32 v76, v65
	v_pk_fma_f32 v[58:59], v[46:47], v[76:77], v[58:59] op_sel_hi:[0,1,1] neg_lo:[1,0,0] neg_hi:[1,0,0]
	v_mov_b32_e32 v60, v66
	v_mov_b32_e32 v61, v78
	v_pk_fma_f32 v[58:59], v[48:49], v[60:61], v[58:59] op_sel:[1,0,0] neg_lo:[1,0,0] neg_hi:[1,0,0]
	v_mov_b32_e32 v78, v67
	v_mov_b32_e32 v66, v51
	v_pk_fma_f32 v[58:59], v[66:67], v[78:79], v[58:59] op_sel_hi:[0,1,1] neg_lo:[1,0,0] neg_hi:[1,0,0]
	v_mov_b32_e32 v60, v68
	v_mov_b32_e32 v61, v80
	v_mov_b32_e32 v68, v53
	v_pk_fma_f32 v[58:59], v[68:69], v[60:61], v[58:59] op_sel_hi:[0,1,1] neg_lo:[1,0,0] neg_hi:[1,0,0]
	v_mov_b32_e32 v80, v69
	v_pk_fma_f32 v[58:59], v[80:81], v[54:55], v[58:59] op_sel_hi:[1,0,1] neg_lo:[1,0,0] neg_hi:[1,0,0]
	v_cndmask_b32_e64 v21, 0, 1.0, vcc
	v_fma_f32 v61, -v82, v59, v58
	v_mov_b32_e32 v60, v59
	v_lshl_add_u32 v5, v1, 2, s3
	ds_read_b128 v[62:65], v5 offset:9888
	ds_read_b128 v[70:73], v5 offset:9904
	ds_read_b128 v[74:77], v5 offset:9920
	ds_read_b128 v[78:81], v5 offset:9936
	v_mov_b32_e32 v55, v59
	v_cmp_eq_u32_e32 vcc, 28, v152
	v_mov_b32_e32 v35, 0
	s_waitcnt lgkmcnt(3)
; #define LAS __attribute__((address_space(3)))
; __device__ __forceinline__ void delta_prep_wave(const Params& P, LAS unsigned char* lds, int idx, int wave, int lane) {
;     ...
;     { int loff = hh * 1152;
;       float x[32];
; #pragma unroll
;       for (int i = 0; i < 32; ++i) { float sacc = (i == n) ? 1.f : 0.f;
;           const LAS float* Lb = Lm + loff;
; #pragma unroll
;           for (int j4 = 0; j4 < (i + 3) / 4; ++j4) { const f32x4 l = *(const LAS f32x4*)(Lb + i * 36 + 4 * j4);
; #pragma unroll
;               for (int jj = 0; jj < 4; ++jj) if (4 * j4 + jj < i) sacc -= l[jj] * x[4 * j4 + jj]; }
;           x[i] = sacc;
;           if ((i & 1) == 1) asm volatile("" : "+v"(loff) : "v"(sacc)); }
	v_fma_f32 v27, -v0, v62, v27
	v_fma_f32 v27, -v2, v63, v27
	v_fma_f32 v27, -v3, v64, v27
	v_fma_f32 v27, -v4, v65, v27
	s_waitcnt lgkmcnt(2)
	v_fma_f32 v27, -v7, v70, v27
	v_fma_f32 v27, -v9, v71, v27
	v_fma_f32 v27, -v11, v72, v27
	v_fma_f32 v27, -v12, v73, v27
	s_waitcnt lgkmcnt(1)
	v_fma_f32 v27, -v15, v74, v27
	ds_read_b128 v[62:65], v5 offset:9952
	ds_read_b128 v[70:73], v5 offset:9968
	v_fma_f32 v27, -v17, v75, v27
	v_fma_f32 v27, -v19, v76, v27
	v_fma_f32 v27, -v20, v77, v27
	s_waitcnt lgkmcnt(2)
	v_fma_f32 v27, -v23, v78, v27
	v_fma_f32 v27, -v25, v79, v27
	s_waitcnt lgkmcnt(1)
	v_pk_mov_b32 v[74:75], v[80:81], v[62:63] op_sel:[1,0]
	v_fma_f32 v27, -v29, v80, v27
	v_pk_mul_f32 v[74:75], v[30:31], v[74:75]
	ds_read_b128 v[78:81], v5 offset:10096
	v_sub_f32_e32 v27, v27, v74
	v_sub_f32_e32 v27, v27, v75
	v_fma_f32 v27, -v43, v63, v27
	v_pk_mul_f32 v[62:63], v[56:57], v[64:65]
	v_mov_b32_e32 v64, v53
	v_sub_f32_e32 v27, v27, v62
	v_sub_f32_e32 v27, v27, v63
	s_waitcnt lgkmcnt(1)
	v_pk_mul_f32 v[62:63], v[50:51], v[70:71]
	v_mov_b32_e32 v65, v54
	v_sub_f32_e32 v27, v27, v62
	ds_read_b64 v[74:75], v5 offset:9984
	v_sub_f32_e32 v27, v27, v63
	v_pk_mul_f32 v[62:63], v[64:65], v[72:73]
	ds_read_b128 v[70:73], v5 offset:10032
	v_sub_f32_e32 v27, v27, v62
	v_sub_f32_e32 v27, v27, v63
	s_waitcnt lgkmcnt(1)
	v_pk_mul_f32 v[62:63], v[74:75], v[60:61]
	ds_read_b128 v[74:77], v5 offset:10048
	s_waitcnt lgkmcnt(1)
	v_fma_f32 v13, -v0, v70, v13
	v_fma_f32 v13, -v2, v71, v13
	v_fma_f32 v13, -v3, v72, v13
	v_fma_f32 v13, -v4, v73, v13
	ds_read_b128 v[70:73], v5 offset:10064
	s_waitcnt lgkmcnt(1)
	v_fma_f32 v13, -v7, v74, v13
	v_fma_f32 v13, -v9, v75, v13
	v_fma_f32 v13, -v11, v76, v13
	v_fma_f32 v13, -v12, v77, v13
	ds_read_b128 v[74:77], v5 offset:10080
	s_waitcnt lgkmcnt(1)
	v_fma_f32 v13, -v15, v70, v13
	v_fma_f32 v13, -v17, v71, v13
	v_fma_f32 v13, -v19, v72, v13
	v_fma_f32 v13, -v20, v73, v13
	s_waitcnt lgkmcnt(0)
	v_fma_f32 v13, -v23, v74, v13
	v_fma_f32 v13, -v25, v75, v13
	v_pk_mov_b32 v[70:71], v[76:77], v[78:79] op_sel:[1,0]
	v_fma_f32 v13, -v29, v76, v13
	v_pk_mul_f32 v[70:71], v[30:31], v[70:71]
	v_mov_b32_e32 v74, v79
	v_sub_f32_e32 v13, v13, v70
	v_sub_f32_e32 v13, v13, v71
	ds_read_b128 v[70:73], v5 offset:10112
	v_mov_b32_e32 v75, v80
	v_pk_mul_f32 v[74:75], v[44:45], v[74:75]
	v_sub_f32_e32 v27, v27, v62
	v_sub_f32_e32 v13, v13, v74
	v_sub_f32_e32 v13, v13, v75
	ds_read_b128 v[74:77], v5 offset:10128
	s_waitcnt lgkmcnt(1)
	v_pk_mov_b32 v[78:79], v[80:81], v[70:71] op_sel:[1,0]
	v_mov_b32_e32 v70, v71
	v_pk_mul_f32 v[78:79], v[46:47], v[78:79]
	v_mov_b32_e32 v71, v72
	v_sub_f32_e32 v5, v13, v78
	v_sub_f32_e32 v5, v5, v79
	v_pk_mul_f32 v[70:71], v[52:53], v[70:71]
	v_sub_f32_e32 v63, v27, v63
	v_sub_f32_e32 v5, v5, v70
	v_sub_f32_e32 v5, v5, v71
	s_waitcnt lgkmcnt(0)
	v_pk_mov_b32 v[70:71], v[72:73], v[74:75] op_sel:[1,0]
	v_mov_b32_e32 v62, v61
	v_pk_mul_f32 v[70:71], v[54:55], v[70:71]
	v_cndmask_b32_e64 v107, 0, 1.0, vcc
	v_sub_f32_e32 v5, v5, v70
	v_sub_f32_e32 v5, v5, v71
	v_mov_b32_e32 v70, v75
	v_mov_b32_e32 v71, v76
	v_pk_mul_f32 v[70:71], v[70:71], v[62:63]
	v_cmp_eq_u32_e32 vcc, 29, v152
	v_sub_f32_e32 v5, v5, v70
	v_sub_f32_e32 v28, v5, v71
	v_cndmask_b32_e64 v106, 0, 1.0, vcc
	v_lshl_add_u32 v5, v1, 2, s3
	ds_read_b128 v[70:73], v5 offset:10176
	ds_read_b128 v[74:77], v5 offset:10192
	ds_read_b128 v[78:81], v5 offset:10208
	ds_read_b128 v[82:85], v5 offset:10224
	ds_read_b128 v[86:89], v5 offset:10240
	ds_read_b128 v[90:93], v5 offset:10256
	ds_read_b128 v[94:97], v5 offset:10272
	ds_read_b128 v[98:101], v5 offset:10320
	ds_read_b128 v[102:105], v5 offset:10336
	s_waitcnt lgkmcnt(8)
	v_mov_b32_e32 v109, v70
	v_cmp_eq_u32_e32 vcc, 31, v152
	v_lshl_add_u64 v[32:33], v[32:33], 0, v[34:35]
	s_waitcnt lgkmcnt(1)
	v_mov_b32_e32 v108, v98
	v_pk_fma_f32 v[106:107], v[0:1], v[108:109], v[106:107] op_sel_hi:[0,1,1] neg_lo:[1,0,0] neg_hi:[1,0,0]
	v_mov_b32_e32 v70, v99
	v_pk_fma_f32 v[70:71], v[2:3], v[70:71], v[106:107] op_sel_hi:[0,1,1] neg_lo:[1,0,0] neg_hi:[1,0,0]
	v_mov_b32_e32 v98, v100
	v_mov_b32_e32 v99, v72
	v_pk_fma_f32 v[26:27], v[26:27], v[98:99], v[70:71] op_sel_hi:[0,1,1] neg_lo:[1,0,0] neg_hi:[1,0,0]
	v_mov_b32_e32 v72, v101
	v_pk_fma_f32 v[26:27], v[4:5], v[72:73], v[26:27] op_sel_hi:[0,1,1] neg_lo:[1,0,0] neg_hi:[1,0,0]
	ds_read_b128 v[70:73], v5 offset:10352
	s_waitcnt lgkmcnt(1)
	v_mov_b32_e32 v98, v102
	v_mov_b32_e32 v99, v74
	v_pk_fma_f32 v[26:27], v[6:7], v[98:99], v[26:27] op_sel:[1,0,0] neg_lo:[1,0,0] neg_hi:[1,0,0]
	v_mov_b32_e32 v74, v103
	v_pk_fma_f32 v[26:27], v[36:37], v[74:75], v[26:27] op_sel_hi:[0,1,1] neg_lo:[1,0,0] neg_hi:[1,0,0]
	v_mov_b32_e32 v36, v104
	v_mov_b32_e32 v37, v76
	ds_read_b128 v[98:101], v5 offset:10368
	v_pk_fma_f32 v[26:27], v[38:39], v[36:37], v[26:27] op_sel_hi:[0,1,1] neg_lo:[1,0,0] neg_hi:[1,0,0]
	v_mov_b32_e32 v76, v105
	v_pk_fma_f32 v[26:27], v[12:13], v[76:77], v[26:27] op_sel_hi:[0,1,1] neg_lo:[1,0,0] neg_hi:[1,0,0]
	s_waitcnt lgkmcnt(1)
	v_mov_b32_e32 v36, v70
	v_mov_b32_e32 v37, v78
	v_pk_fma_f32 v[26:27], v[14:15], v[36:37], v[26:27] op_sel:[1,0,0] neg_lo:[1,0,0] neg_hi:[1,0,0]
	v_mov_b32_e32 v78, v71
	v_pk_fma_f32 v[26:27], v[8:9], v[78:79], v[26:27] op_sel_hi:[0,1,1] neg_lo:[1,0,0] neg_hi:[1,0,0]
	v_mov_b32_e32 v36, v72
	v_mov_b32_e32 v37, v80
	v_pk_fma_f32 v[26:27], v[16:17], v[36:37], v[26:27] op_sel_hi:[0,1,1] neg_lo:[1,0,0] neg_hi:[1,0,0]
	v_mov_b32_e32 v80, v73
	ds_read_b128 v[36:39], v5 offset:10384
	v_pk_fma_f32 v[26:27], v[20:21], v[80:81], v[26:27] op_sel_hi:[0,1,1] neg_lo:[1,0,0] neg_hi:[1,0,0]
	s_waitcnt lgkmcnt(1)
; #define LAS __attribute__((address_space(3)))
; __device__ __forceinline__ void delta_prep_wave(const Params& P, LAS unsigned char* lds, int idx, int wave, int lane) {
;     ...
;     { int loff = hh * 1152;
;       float x[32];
; #pragma unroll
;       for (int i = 0; i < 32; ++i) { float sacc = (i == n) ? 1.f : 0.f;
;           const LAS float* Lb = Lm + loff;
; #pragma unroll
;           for (int j4 = 0; j4 < (i + 3) / 4; ++j4) { const f32x4 l = *(const LAS f32x4*)(Lb + i * 36 + 4 * j4);
; #pragma unroll
;               for (int jj = 0; jj < 4; ++jj) if (4 * j4 + jj < i) sacc -= l[jj] * x[4 * j4 + jj]; }
;           x[i] = sacc;
;           if ((i & 1) == 1) asm volatile("" : "+v"(loff) : "v"(sacc)); }
	v_mov_b32_e32 v70, v98
	v_mov_b32_e32 v71, v82
	v_pk_fma_f32 v[26:27], v[22:23], v[70:71], v[26:27] op_sel:[1,0,0] neg_lo:[1,0,0] neg_hi:[1,0,0]
	v_mov_b32_e32 v82, v99
	v_pk_fma_f32 v[26:27], v[10:11], v[82:83], v[26:27] op_sel_hi:[0,1,1] neg_lo:[1,0,0] neg_hi:[1,0,0]
	v_mov_b32_e32 v70, v100
	v_mov_b32_e32 v71, v84
	v_pk_fma_f32 v[26:27], v[24:25], v[70:71], v[26:27] op_sel_hi:[0,1,1] neg_lo:[1,0,0] neg_hi:[1,0,0]
	v_mov_b32_e32 v84, v101
	v_pk_fma_f32 v[26:27], v[30:31], v[84:85], v[26:27] op_sel_hi:[0,1,1] neg_lo:[1,0,0] neg_hi:[1,0,0]
	s_waitcnt lgkmcnt(0)
	v_mov_b32_e32 v82, v36
	v_mov_b32_e32 v83, v86
	ds_read_b128 v[70:73], v5 offset:10400
	ds_read_b128 v[74:77], v5 offset:10416
	ds_read_b128 v[78:81], v5 offset:10432
	v_pk_fma_f32 v[26:27], v[40:41], v[82:83], v[26:27] op_sel:[1,0,0] neg_lo:[1,0,0] neg_hi:[1,0,0]
	v_mov_b32_e32 v86, v37
	v_pk_fma_f32 v[26:27], v[18:19], v[86:87], v[26:27] op_sel_hi:[0,1,1] neg_lo:[1,0,0] neg_hi:[1,0,0]
	v_mov_b32_e32 v36, v38
	v_mov_b32_e32 v37, v88
	v_pk_fma_f32 v[26:27], v[42:43], v[36:37], v[26:27] op_sel_hi:[0,1,1] neg_lo:[1,0,0] neg_hi:[1,0,0]
	v_mov_b32_e32 v88, v39
	v_pk_fma_f32 v[26:27], v[46:47], v[88:89], v[26:27] op_sel_hi:[0,1,1] neg_lo:[1,0,0] neg_hi:[1,0,0]
	s_waitcnt lgkmcnt(2)
	v_mov_b32_e32 v36, v70
	v_mov_b32_e32 v37, v90
	v_pk_fma_f32 v[26:27], v[48:49], v[36:37], v[26:27] op_sel:[1,0,0] neg_lo:[1,0,0] neg_hi:[1,0,0]
	v_mov_b32_e32 v90, v71
	v_pk_fma_f32 v[26:27], v[66:67], v[90:91], v[26:27] op_sel_hi:[0,1,1] neg_lo:[1,0,0] neg_hi:[1,0,0]
	v_mov_b32_e32 v36, v72
	v_mov_b32_e32 v37, v92
	v_pk_fma_f32 v[26:27], v[68:69], v[36:37], v[26:27] op_sel_hi:[0,1,1] neg_lo:[1,0,0] neg_hi:[1,0,0]
	v_mov_b32_e32 v92, v73
	v_pk_fma_f32 v[26:27], v[54:55], v[92:93], v[26:27] op_sel_hi:[0,1,1] neg_lo:[1,0,0] neg_hi:[1,0,0]
	s_waitcnt lgkmcnt(1)
	v_mov_b32_e32 v36, v74
	v_mov_b32_e32 v37, v94
	v_pk_fma_f32 v[26:27], v[58:59], v[36:37], v[26:27] op_sel:[1,0,0] neg_lo:[1,0,0] neg_hi:[1,0,0]
	v_mov_b32_e32 v94, v75
	v_mov_b32_e32 v6, v61
	v_pk_fma_f32 v[26:27], v[6:7], v[94:95], v[26:27] op_sel_hi:[0,1,1] neg_lo:[1,0,0] neg_hi:[1,0,0]
	v_mov_b32_e32 v36, v76
	v_mov_b32_e32 v37, v96
	v_mov_b32_e32 v6, v63
	v_pk_fma_f32 v[26:27], v[6:7], v[36:37], v[26:27] op_sel_hi:[0,1,1] neg_lo:[1,0,0] neg_hi:[1,0,0]
	v_mov_b32_e32 v96, v77
	v_pk_fma_f32 v[26:27], v[96:97], v[28:29], v[26:27] op_sel_hi:[1,0,1] neg_lo:[1,0,0] neg_hi:[1,0,0]
	v_cndmask_b32_e64 v6, 0, 1.0, vcc
	s_waitcnt lgkmcnt(0)
	v_fma_f32 v79, -v78, v27, v26
	v_mov_b32_e32 v78, v27
	v_lshl_add_u32 v5, v1, 2, s3
	ds_read_b128 v[36:39], v5 offset:10464
	ds_read_b128 v[66:69], v5 offset:10480
	ds_read_b128 v[70:73], v5 offset:10496
	ds_read_b128 v[74:77], v5 offset:10512
	s_mov_b32 s3, 0x1180000
	s_mov_b64 s[4:5], 0x1180000
	v_lshl_add_u64 v[34:35], v[32:33], 0, s[4:5]
	s_waitcnt lgkmcnt(3)
	v_fma_f32 v8, -v0, v36, v21
	v_fma_f32 v8, -v2, v37, v8
	v_fma_f32 v8, -v3, v38, v8
	v_fma_f32 v8, -v4, v39, v8
	s_waitcnt lgkmcnt(2)
	v_fma_f32 v8, -v7, v66, v8
	v_fma_f32 v8, -v9, v67, v8
	v_fma_f32 v8, -v11, v68, v8
	v_fma_f32 v8, -v12, v69, v8
	s_waitcnt lgkmcnt(1)
	v_fma_f32 v8, -v15, v70, v8
	v_fma_f32 v8, -v17, v71, v8
	v_fma_f32 v8, -v19, v72, v8
	v_fma_f32 v8, -v20, v73, v8
	ds_read_b128 v[36:39], v5 offset:10528
	ds_read_b128 v[66:69], v5 offset:10544
	s_waitcnt lgkmcnt(2)
	v_fma_f32 v8, -v23, v74, v8
	v_fma_f32 v8, -v25, v75, v8
	v_fma_f32 v8, -v29, v76, v8
	v_fma_f32 v8, -v30, v77, v8
	s_waitcnt lgkmcnt(1)
	v_fma_f32 v8, -v41, v36, v8
	v_fma_f32 v8, -v43, v37, v8
	v_pk_mul_f32 v[36:37], v[56:57], v[38:39]
	v_mov_b32_e32 v70, v63
	v_sub_f32_e32 v8, v8, v36
	v_sub_f32_e32 v8, v8, v37
	s_waitcnt lgkmcnt(0)
	v_pk_mul_f32 v[36:37], v[50:51], v[66:67]
	v_pk_mul_f32 v[66:67], v[64:65], v[68:69]
	v_sub_f32_e32 v8, v8, v36
	v_sub_f32_e32 v8, v8, v37
	ds_read_b128 v[36:39], v5 offset:10560
	v_sub_f32_e32 v8, v8, v66
	v_sub_f32_e32 v8, v8, v67
	ds_read_b64 v[66:67], v5 offset:10576
	v_mov_b32_e32 v71, v28
	s_waitcnt lgkmcnt(1)
	v_pk_mul_f32 v[36:37], v[60:61], v[36:37]
	v_mov_b32_e32 v72, v79
	v_sub_f32_e32 v8, v8, v36
	v_sub_f32_e32 v8, v8, v37
	v_pk_mul_f32 v[36:37], v[70:71], v[38:39]
	s_waitcnt lgkmcnt(0)
	v_pk_mul_f32 v[66:67], v[66:67], v[78:79]
	v_sub_f32_e32 v8, v8, v36
	v_sub_f32_e32 v8, v8, v37
	ds_read_b128 v[36:39], v5 offset:10608
	v_sub_f32_e32 v8, v8, v66
	v_sub_f32_e32 v73, v8, v67
	ds_read_b128 v[66:69], v5 offset:10624
	s_cselect_b64 s[6:7], -1, 0
	s_waitcnt lgkmcnt(1)
	v_fma_f32 v6, -v0, v36, v6
	v_fma_f32 v6, -v2, v37, v6
	v_fma_f32 v6, -v3, v38, v6
	v_fma_f32 v6, -v4, v39, v6
	ds_read_b128 v[36:39], v5 offset:10640
	s_waitcnt lgkmcnt(1)
	v_fma_f32 v6, -v7, v66, v6
	v_fma_f32 v6, -v9, v67, v6
	v_fma_f32 v6, -v11, v68, v6
	v_fma_f32 v6, -v12, v69, v6
	ds_read_b128 v[66:69], v5 offset:10656
	s_waitcnt lgkmcnt(1)
	v_fma_f32 v6, -v15, v36, v6
	v_fma_f32 v6, -v17, v37, v6
	v_fma_f32 v6, -v19, v38, v6
	v_fma_f32 v6, -v20, v39, v6
	s_waitcnt lgkmcnt(0)
; __device__ __forceinline__ unsigned f2bf(float f) { return pk2(f, f) & 0xffffu; }
; #define LDS_WAIT() asm volatile("s_waitcnt lgkmcnt(0)" ::: "memory")
; __device__ __forceinline__ int perm16(int e) { return (e & ~12) | ((e >> 1) & 4) | ((e << 1) & 8); }
; #define lane opq(lane_now())
; #define tid opq((wave << 6) | lane_now())
; __device__ __forceinline__ void delta_prep_wave(const Params& P, LAS unsigned char* lds, int idx, int wave, int lane) {
;     ...
;       bf16* ti = TINV + ((size_t)bh * 64 + span * 2 + hh) * 1024 + perm16(n);
; #pragma unroll
;       for (int i = 0; i < 32; ++i) ti[i * 32] = (bf16)f2bf(x[i]); }
;     LDS_WAIT(); asm volatile("" ::: "memory");
; __global__ void __launch_bounds__(NTHR, 2) fwd_megakernel(Params P) {
;     ...
;           delta_prep_wave(P, lds, gw, wave, lane);
;           __syncthreads(); }
;         if (G == 256) { const int task = (wg & 7) * 32 + (wg >> 3); rglru_task(P, lds, task >> 5, (task >> 2) & 7, task & 3, tid, 0, RG_SPLIT); }
;         else for (int task = wg; task < 256; task += G) rglru_task(P, lds, task >> 5, (task >> 2) & 7, task & 3, tid, 0, RG_SPLIT);
	v_fma_f32 v6, -v23, v66, v6
	ds_read_b128 v[36:39], v5 offset:10672
	v_fma_f32 v6, -v25, v67, v6
	v_fma_f32 v6, -v29, v68, v6
	v_fma_f32 v6, -v30, v69, v6
	ds_read_b128 v[66:69], v5 offset:10688
	s_waitcnt lgkmcnt(1)
	v_fma_f32 v6, -v41, v36, v6
	v_fma_f32 v6, -v43, v37, v6
	v_pk_mul_f32 v[36:37], v[56:57], v[38:39]
	s_cmpk_lg_i32 s78, 0x100
	v_sub_f32_e32 v6, v6, v36
	v_sub_f32_e32 v6, v6, v37
	s_waitcnt lgkmcnt(0)
	v_pk_mul_f32 v[36:37], v[50:51], v[66:67]
	v_pk_mul_f32 v[56:57], v[64:65], v[68:69]
	v_sub_f32_e32 v6, v6, v36
	v_sub_f32_e32 v6, v6, v37
	ds_read_b128 v[36:39], v5 offset:10704
	ds_read_b128 v[64:67], v5 offset:10720
	v_sub_f32_e32 v6, v6, v56
	v_sub_f32_e32 v6, v6, v57
	s_cselect_b64 s[4:5], -1, 0
	s_waitcnt lgkmcnt(1)
	v_pk_mul_f32 v[36:37], v[60:61], v[36:37]
	v_writelane_b32 v238, s4, 21
	v_sub_f32_e32 v5, v6, v36
	v_sub_f32_e32 v5, v5, v37
	v_pk_mul_f32 v[36:37], v[70:71], v[38:39]
	v_cvt_pk_bf16_f32 v6, v0, s0
	v_sub_f32_e32 v5, v5, v36
	v_sub_f32_e32 v5, v5, v37
	s_waitcnt lgkmcnt(0)
	v_mov_b32_e32 v36, v65
	v_mov_b32_e32 v37, v66
	v_fma_f32 v5, -v27, v64, v5
	v_pk_mul_f32 v[36:37], v[36:37], v[72:73]
	v_add_co_u32_e32 v0, vcc, s3, v32
	v_sub_f32_e32 v5, v5, v36
	v_sub_f32_e32 v5, v5, v37
	v_writelane_b32 v238, s5, 22
	v_addc_co_u32_e32 v1, vcc, 0, v33, vcc
	global_store_short v[0:1], v6, off
	v_cvt_pk_bf16_f32 v0, v2, s0
	global_store_short v[34:35], v0, off offset:64
	v_cvt_pk_bf16_f32 v0, v3, s0
	global_store_short v[34:35], v0, off offset:128
	v_cvt_pk_bf16_f32 v0, v4, s0
	global_store_short v[34:35], v0, off offset:192
	v_cvt_pk_bf16_f32 v0, v7, s0
	global_store_short v[34:35], v0, off offset:256
	v_cvt_pk_bf16_f32 v0, v9, s0
	global_store_short v[34:35], v0, off offset:320
	v_cvt_pk_bf16_f32 v0, v11, s0
	global_store_short v[34:35], v0, off offset:384
	v_cvt_pk_bf16_f32 v0, v12, s0
	global_store_short v[34:35], v0, off offset:448
	v_cvt_pk_bf16_f32 v0, v15, s0
	global_store_short v[34:35], v0, off offset:512
	v_cvt_pk_bf16_f32 v0, v17, s0
	global_store_short v[34:35], v0, off offset:576
	v_cvt_pk_bf16_f32 v0, v19, s0
	global_store_short v[34:35], v0, off offset:640
	v_cvt_pk_bf16_f32 v0, v20, s0
	global_store_short v[34:35], v0, off offset:704
	v_cvt_pk_bf16_f32 v0, v23, s0
	global_store_short v[34:35], v0, off offset:768
	v_cvt_pk_bf16_f32 v0, v25, s0
	global_store_short v[34:35], v0, off offset:832
	v_cvt_pk_bf16_f32 v0, v29, s0
	global_store_short v[34:35], v0, off offset:896
	v_cvt_pk_bf16_f32 v0, v30, s0
	global_store_short v[34:35], v0, off offset:960
	v_cvt_pk_bf16_f32 v0, v41, s0
	global_store_short v[34:35], v0, off offset:1024
	v_cvt_pk_bf16_f32 v0, v43, s0
	global_store_short v[34:35], v0, off offset:1088
	v_cvt_pk_bf16_f32 v0, v45, s0
	global_store_short v[34:35], v0, off offset:1152
	v_cvt_pk_bf16_f32 v0, v46, s0
	global_store_short v[34:35], v0, off offset:1216
	v_cvt_pk_bf16_f32 v0, v49, s0
	global_store_short v[34:35], v0, off offset:1280
	v_cvt_pk_bf16_f32 v0, v51, s0
	global_store_short v[34:35], v0, off offset:1344
	v_cvt_pk_bf16_f32 v0, v53, s0
	global_store_short v[34:35], v0, off offset:1408
	v_cvt_pk_bf16_f32 v0, v54, s0
	global_store_short v[34:35], v0, off offset:1472
	v_cvt_pk_bf16_f32 v0, v59, s0
	global_store_short v[34:35], v0, off offset:1536
	v_cvt_pk_bf16_f32 v0, v61, s0
	global_store_short v[34:35], v0, off offset:1600
	v_cvt_pk_bf16_f32 v0, v63, s0
	global_store_short v[34:35], v0, off offset:1664
	v_cvt_pk_bf16_f32 v0, v28, s0
	global_store_short v[34:35], v0, off offset:1728
	v_cvt_pk_bf16_f32 v0, v27, s0
	global_store_short v[34:35], v0, off offset:1792
	v_cvt_pk_bf16_f32 v0, v79, s0
	global_store_short v[34:35], v0, off offset:1856
	v_cvt_pk_bf16_f32 v0, v73, s0
	global_store_short v[34:35], v0, off offset:1920
	v_cvt_pk_bf16_f32 v0, v5, s0
	global_store_short v[34:35], v0, off offset:1984
	s_waitcnt lgkmcnt(0)
	s_mov_b64 s[4:5], -1
	v_writelane_b32 v238, s6, 18
	s_and_b64 vcc, exec, s[6:7]
	s_barrier
	v_writelane_b32 v238, s7, 19
	s_cmp_eq_u32 s98, 2
	s_cbranch_scc1 .LBB0_1410
	s_cbranch_vccnz .LBB0_1262
	v_readlane_b32 s4, v238, 10
	v_readlane_b32 s5, v238, 11
	s_and_b64 vcc, exec, s[4:5]
	s_cbranch_vccnz .LBB0_1261
	s_mov_b32 s57, 0
	v_mov_b32_e32 v16, 0
	s_add_i32 s3, 0, 0x15880
	v_mov_b32_e32 v75, 0xa0
	v_mov_b32_e32 v150, 0x90
	v_mov_b32_e32 v151, 0x3ecc95a3
	s_movk_i32 s70, 0x830
	s_movk_i32 s71, 0x630
	s_movk_i32 s72, 0x430
	s_movk_i32 s73, 0x230
	s_add_i32 s83, 0, 0x16280
	s_movk_i32 s88, 0x110
	s_add_i32 s89, 0, 0xc800
	s_add_i32 s90, 0, 0x10800
	s_add_i32 s91, 0, 0x14800
	s_add_i32 s94, 0, 0x15000
	s_movk_i32 s95, 0xc00
	s_movk_i32 s96, 0x1000
	v_mov_b32_e32 v152, 0x3c088889
	s_mov_b32 s97, 0xbe99999a
	v_mov_b32_e32 v72, 0x3f317218
	v_mov_b32_e32 v153, 0x7f800000
	v_mov_b32_e32 v154, 0x7fc00000
	v_mov_b32_e32 v155, 0xff800000
	v_mov_b32_e32 v156, 0x8800
	s_mov_b32 s60, s2
	s_branch .LBB0_1111

; __device__ __forceinline__ unsigned char* karg_ws() { return *(volatile KAS ucptr_t*)((const KAS char*)__builtin_amdgcn_kernarg_segment_ptr() + 264); }
; #define INP(k) karg_in(k)
; #define tid opq((wave << 6) | lane_now())
; __device__ __forceinline__ void rglru_task(const Params& P, LAS unsigned char* lds, int b, int n, int qd, int tid, int t0, int t1) {
;     ...
;     bf16* XR = (bf16*)(karg_ws() + WS_Z); bf16* GR = (bf16*)(karg_ws() + WS_Z + ZB);
;     const bf16* WRG = (const bf16*)(karg_ws() + WS_WRG);
;     const int cb0 = n * 128, oc0 = cb0 + qd * 32;
;     const bool prompt = b >= 0;
;     for (int i = tid; i < 640; i += NTHR) cw[i] = i < 512 ? INP(15)[(size_t)(i >> 7) * D + cb0 + (i & 127)] : INP(16)[cb0 + (i - 512)];
; __global__ void __launch_bounds__(NTHR, 2) fwd_megakernel(Params P) {
;     ...
;         if (G == 256) { const int task = (wg & 7) * 32 + (wg >> 3); rglru_task(P, lds, task >> 5, (task >> 2) & 7, task & 3, tid, 0, RG_SPLIT); }
.Lp7a_rg:
	v_mov_b32_e32 v6, v167
	s_load_dwordx2 s[52:53], s[0:1], 0x108
	s_load_dwordx2 s[4:5], s[0:1], 0x108
	s_load_dwordx2 s[8:9], s[0:1], 0x108
	s_bfe_u32 s3, s2, 0x30005
	s_movk_i32 s7, 0x280
	s_lshl_b32 s6, s3, 7
	v_cmp_gt_i32_e32 vcc, s7, v6
	v_lshl_add_u32 v4, v6, 2, 0
	s_and_saveexec_b64 s[10:11], vcc
	s_cbranch_execz .LBB0_1270
	v_and_b32_e32 v0, 0x7f, v6
	s_mov_b32 s13, 0
	s_movk_i32 s7, 0x7f
	v_mov_b32_e32 v1, 0
	v_add_u32_e32 v8, 0xfffffe00, v6
	v_add_u32_e32 v5, 0x15880, v4
	s_mov_b64 s[14:15], 0
	s_movk_i32 s18, 0x1ff
	s_lshl_b32 s12, s6, 2
	v_lshlrev_b32_e32 v0, 2, v0
	s_branch .LBB0_1266

; __device__ __forceinline__ float* karg_out() { return *(volatile KAS fptr_t*)((const KAS char*)__builtin_amdgcn_kernarg_segment_ptr() + 256); }
; __device__ __forceinline__ unsigned char* karg_ws() { return *(volatile KAS ucptr_t*)((const KAS char*)__builtin_amdgcn_kernarg_segment_ptr() + 264); }
; #define RG_RAW_STORE() do { _Pragma("unroll") for (int i = 0; i < 5; ++i) { const int q = tid + 512 * i; if (q < 131 * 16) *(LAS u32x4*)(rawt + (q >> 4) * 136 + (q & 15) * 8) = pre[i]; } } while (0)
; __device__ __forceinline__ void rglru_task(const Params& P, LAS unsigned char* lds, int b, int n, int qd, int tid, int t0, int t1) {
;     ...
;         if (prompt && tile + 1 < ntiles) RG_RAW_STORE();
;         __syncthreads();
;         if (prompt && seg == 15) hc[ch] = hlast;
;     }
;     if (prompt && seg == 15) { if (t1 == 16) karg_out()[O_HP + (size_t)b * D + oc0 + ch] = hlast; else ((float*)(karg_ws() + WS_HCARRY))[(size_t)b * D + oc0 + ch] = hlast; }
;     __syncthreads();
.LBB0_1409:
	s_or_b64 exec, exec, s[4:5]
	s_waitcnt lgkmcnt(0)
	s_barrier
	s_cmp_eq_u32 s98, 1
	s_cbranch_scc0 .LBB0_1410
	s_mov_b32 s98, 2
	s_lshr_b32 s3, s83, 6
	s_branch .Lp7a_prep

; __global__ void __launch_bounds__(NTHR, 2) fwd_megakernel(Params P) {
	.amdhsa_kernel _Z14fwd_megakernel6Params
		.amdhsa_group_segment_fixed_size 0
		.amdhsa_private_segment_fixed_size 0
		.amdhsa_kernarg_size 528
		.amdhsa_user_sgpr_count 2
		.amdhsa_user_sgpr_dispatch_ptr 0
		.amdhsa_user_sgpr_queue_ptr 0
		.amdhsa_user_sgpr_kernarg_segment_ptr 1
		.amdhsa_user_sgpr_dispatch_id 0
		.amdhsa_user_sgpr_kernarg_preload_length 0
		.amdhsa_user_sgpr_kernarg_preload_offset 0
		.amdhsa_user_sgpr_private_segment_size 0
		.amdhsa_uses_dynamic_stack 0
		.amdhsa_enable_private_segment 0
		.amdhsa_system_sgpr_workgroup_id_x 1
		.amdhsa_system_sgpr_workgroup_id_y 0
		.amdhsa_system_sgpr_workgroup_id_z 0
		.amdhsa_system_sgpr_workgroup_info 0
		.amdhsa_system_vgpr_workitem_id 0
		.amdhsa_next_free_vgpr 256
		.amdhsa_next_free_sgpr 102
		.amdhsa_accum_offset 256
		.amdhsa_reserve_vcc 1
		.amdhsa_float_round_mode_32 0
		.amdhsa_float_round_mode_16_64 0
		.amdhsa_float_denorm_mode_32 3
		.amdhsa_float_denorm_mode_16_64 3
		.amdhsa_dx10_clamp 1
		.amdhsa_ieee_mode 1
		.amdhsa_fp16_overflow 0
		.amdhsa_tg_split 0
		.amdhsa_exception_fp_ieee_invalid_op 0
		.amdhsa_exception_fp_denorm_src 0
		.amdhsa_exception_fp_ieee_div_zero 0
		.amdhsa_exception_fp_ieee_overflow 0
		.amdhsa_exception_fp_ieee_underflow 0
		.amdhsa_exception_fp_ieee_inexact 0
		.amdhsa_exception_int_div_zero 0
	.end_amdhsa_kernel

; __global__ void __launch_bounds__(NTHR, 2) fwd_megakernel(Params P) {
amdhsa.kernels:
  - .agpr_count:     0
    .args:
      - .offset:         0
        .size:           272
        .value_kind:     by_value
      - .offset:         272
        .size:           4
        .value_kind:     hidden_block_count_x
      - .offset:         276
        .size:           4
        .value_kind:     hidden_block_count_y
      - .offset:         280
        .size:           4
        .value_kind:     hidden_block_count_z
      - .offset:         284
        .size:           2
        .value_kind:     hidden_group_size_x
      - .offset:         286
        .size:           2
        .value_kind:     hidden_group_size_y
      - .offset:         288
        .size:           2
        .value_kind:     hidden_group_size_z
      - .offset:         290
        .size:           2
        .value_kind:     hidden_remainder_x
      - .offset:         292
        .size:           2
        .value_kind:     hidden_remainder_y
      - .offset:         294
        .size:           2
        .value_kind:     hidden_remainder_z
      - .offset:         312
        .size:           8
        .value_kind:     hidden_global_offset_x
      - .offset:         320
        .size:           8
        .value_kind:     hidden_global_offset_y
      - .offset:         328
        .size:           8
        .value_kind:     hidden_global_offset_z
      - .offset:         336
        .size:           2
        .value_kind:     hidden_grid_dims
      - .offset:         392
        .size:           4
        .value_kind:     hidden_dynamic_lds_size
    .group_segment_fixed_size: 0
    .kernarg_segment_align: 8
    .kernarg_segment_size: 528
    .language:       OpenCL C
    .language_version:
      - 2
      - 0
    .max_flat_workgroup_size: 512
    .name:           _Z14fwd_megakernel6Params
    .private_segment_fixed_size: 0
    .sgpr_count:     108
    .sgpr_spill_count: 26
    .symbol:         _Z14fwd_megakernel6Params.kd
    .uniform_work_group_size: 1
    .uses_dynamic_stack: false
    .vgpr_count:     256
    .vgpr_spill_count: 0
    .wavefront_size: 64
